# bundle: weight-conversion pieces rotated across waves between jobs (same pieces, evenly spread) plus the DPP / permlane-swap lane exchanges, on top of the best bundle
# speedup vs baseline: 1.0019x; 1.0019x over previous
.LBB0_33:
	s_or_b64 exec, exec, s[0:1]
	s_movk_i32 s0, 0x180
	s_cmp_lg_u32 s3, 0x680
	s_cbranch_scc1 .Lp0_rot_skip_802
	v_add_u32_e32 v22, 1280, v22
	v_subrev_u32_e32 v210, s3, v22
	v_cmp_le_u32_e32 vcc, s3, v22
	s_nop 1
	v_cndmask_b32_e32 v22, v22, v210, vcc
.Lp0_rot_skip_802:
	v_cmp_gt_i32_e32 vcc, s0, v22
	s_and_saveexec_b64 s[4:5], vcc
	s_cbranch_execz .LBB0_41
	v_readlane_b32 s68, v241, 17
	v_readlane_b32 s80, v241, 29
	v_readlane_b32 s81, v241, 30
	s_cmp_lg_u64 s[80:81], 0
	s_cselect_b64 s[0:1], -1, 0
	v_lshlrev_b32_e32 v0, 6, v22
	v_cndmask_b32_e64 v1, 0, 1, s[0:1]
	s_mov_b64 s[6:7], 0
	v_or_b32_e32 v0, v0, v142
	s_lshl_b32 s9, s3, 6
	v_cmp_ne_u32_e64 s[0:1], 1, v1
	s_mov_b32 s8, 0x3e16c740
	v_mov_b32_e32 v1, v22
	v_readlane_b32 s69, v241, 18
	v_readlane_b32 s70, v241, 19
	v_readlane_b32 s71, v241, 20
	v_readlane_b32 s72, v241, 21
	v_readlane_b32 s73, v241, 22
	v_readlane_b32 s74, v241, 23
	v_readlane_b32 s75, v241, 24
	v_readlane_b32 s76, v241, 25
	v_readlane_b32 s77, v241, 26
	v_readlane_b32 s78, v241, 27
	v_readlane_b32 s79, v241, 28
	v_readlane_b32 s82, v241, 31
	v_readlane_b32 s83, v241, 32
	s_branch .LBB0_38

.LBB0_41:
	s_or_b64 exec, exec, s[4:5]
	s_movk_i32 s0, 0x100
	s_cmp_lg_u32 s3, 0x680
	s_cbranch_scc1 .Lp0_rot_skip_953
	v_add_u32_e32 v22, 1280, v22
	v_subrev_u32_e32 v210, s3, v22
	v_cmp_le_u32_e32 vcc, s3, v22
	s_nop 1
	v_cndmask_b32_e32 v22, v22, v210, vcc
.Lp0_rot_skip_953:
	v_cmp_gt_i32_e32 vcc, s0, v22
	s_and_saveexec_b64 s[4:5], vcc
	s_cbranch_execz .LBB0_49
	v_readlane_b32 s36, v241, 33
	v_readlane_b32 s37, v241, 34
	s_cmp_lg_u64 s[36:37], 0
	s_cselect_b64 s[0:1], -1, 0
	v_lshlrev_b32_e32 v0, 6, v22
	v_or_b32_e32 v20, v0, v142
	v_cndmask_b32_e64 v0, 0, 1, s[0:1]
	s_mov_b64 s[6:7], 0
	s_lshl_b32 s10, s3, 6
	v_cmp_ne_u32_e64 s[0:1], 1, v0
	v_mov_b32_e32 v21, v22
	v_readlane_b32 s38, v241, 35
	v_readlane_b32 s39, v241, 36
	v_readlane_b32 s40, v241, 37
	v_readlane_b32 s41, v241, 38
	v_readlane_b32 s42, v241, 39
	v_readlane_b32 s43, v241, 40
	v_readlane_b32 s44, v241, 41
	v_readlane_b32 s45, v241, 42
	v_readlane_b32 s46, v241, 43
	v_readlane_b32 s47, v241, 44
	v_readlane_b32 s48, v241, 45
	v_readlane_b32 s49, v241, 46
	v_readlane_b32 s50, v241, 47
	v_readlane_b32 s51, v241, 48
	s_branch .LBB0_46

.LBB0_49:
	s_or_b64 exec, exec, s[4:5]
	s_cmp_lg_u32 s3, 0x680
	s_cbranch_scc1 .Lp0_rot_skip_1097
	v_add_u32_e32 v22, 1408, v22
	v_subrev_u32_e32 v210, s3, v22
	v_cmp_le_u32_e32 vcc, s3, v22
	s_nop 1
	v_cndmask_b32_e32 v22, v22, v210, vcc
.Lp0_rot_skip_1097:
	v_cmp_lt_i32_e32 vcc, 63, v22
	s_and_saveexec_b64 s[0:1], vcc
	s_xor_b64 s[0:1], exec, s[0:1]
	s_andn2_saveexec_b64 s[0:1], s[0:1]
	s_cbranch_execz .LBB0_59
	v_lshlrev_b32_e32 v0, 6, v22
	v_or_b32_e32 v2, v0, v142
	s_lshl_b32 s8, s3, 6
	s_mov_b64 s[4:5], 0
	v_mov_b32_e32 v3, v2
	v_mov_b32_e32 v4, v22
	s_branch .LBB0_52

.LBB0_59:
	s_or_b64 exec, exec, s[0:1]
	s_movk_i32 s0, 0x3ff
	s_cmp_lg_u32 s3, 0x680
	s_cbranch_scc1 .Lp0_rot_skip_1294
	v_add_u32_e32 v22, 1536, v22
	v_subrev_u32_e32 v210, s3, v22
	v_cmp_le_u32_e32 vcc, s3, v22
	s_nop 1
	v_cndmask_b32_e32 v22, v22, v210, vcc
.Lp0_rot_skip_1294:
	v_cmp_lt_i32_e32 vcc, s0, v22
	s_and_saveexec_b64 s[0:1], vcc
	s_xor_b64 s[0:1], exec, s[0:1]
	s_andn2_saveexec_b64 s[0:1], s[0:1]
	s_cbranch_execz .LBB0_71
	v_lshlrev_b32_e32 v0, 6, v22
	v_or_b32_e32 v2, v0, v142
	s_lshl_b32 s8, s3, 6
	s_mov_b64 s[4:5], 0
	v_mov_b32_e32 v3, v2
	v_mov_b32_e32 v4, v22
	s_branch .LBB0_64

.LBB0_71:
	s_or_b64 exec, exec, s[0:1]
	s_movk_i32 s0, 0x7ff
	s_cmp_lg_u32 s3, 0x680
	s_cbranch_scc1 .Lp0_rot_skip_1500
	v_add_u32_e32 v22, 640, v22
	v_subrev_u32_e32 v210, s3, v22
	v_cmp_le_u32_e32 vcc, s3, v22
	s_nop 1
	v_cndmask_b32_e32 v22, v22, v210, vcc
.Lp0_rot_skip_1500:
	v_cmp_lt_i32_e32 vcc, s0, v22
	s_and_saveexec_b64 s[0:1], vcc
	s_xor_b64 s[0:1], exec, s[0:1]
	s_lshl_b32 s4, s90, 9
	s_or_saveexec_b64 s[0:1], s[0:1]
	v_mov_b32_e32 v165, s4
	s_xor_b64 exec, exec, s[0:1]
	s_cbranch_execz .LBB0_79
	s_lshl_b32 s8, s90, 9
	v_lshlrev_b32_e32 v0, 6, v22
	v_or_b32_e32 v2, v0, v142
	s_lshl_b32 s9, s3, 6
	s_mov_b64 s[4:5], 0
	s_branch .LBB0_76
